# layer-1 w_in bias in the idle tail of the layer-0 w_out phase; the gate/up bias groups behind the context-row fix-up go to the waves without a context row
# speedup vs baseline: 1.0080x; 1.0080x over previous
.LBB0_917:
	s_mov_b32 s95, s90
	s_mov_b32 s96, s70
	s_cmp_lg_u32 s70, 0x100
	s_cbranch_scc1 .Lb8_norot
	s_add_i32 s95, s90, 0xfffffc00
	s_cmp_lt_i32 s95, 0
	s_cselect_b32 s95, 0x7fff, s95
	s_movk_i32 s96, 0x80
.Lb8_norot:
	s_lshl_b32 s10, s95, 2
	s_cmpk_gt_i32 s95, 0x57f
	s_cbranch_scc1 .LBB0_922
	v_ashrrev_i32_e32 v65, 31, v64
	s_waitcnt lgkmcnt(0)
	v_lshl_add_u64 v[0:1], v[64:65], 2, s[8:9]
	s_mov_b64 s[0:1], 0x31000
	v_lshl_add_u64 v[66:67], v[0:1], 0, s[0:1]
	s_mov_b64 s[0:1], 0x37000
	v_lshl_add_u64 v[68:69], v[0:1], 0, s[0:1]
	s_mov_b64 s[0:1], 0x3d000
	v_lshl_add_u64 v[70:71], v[0:1], 0, s[0:1]
	s_mov_b64 s[0:1], 0x43000
	s_lshl_b32 s4, s96, 5
	v_lshl_add_u64 v[72:73], v[0:1], 0, s[0:1]
	s_mov_b64 s[0:1], 0x49000
	s_ashr_i32 s11, s10, 31
	v_lshl_add_u64 v[74:75], v[0:1], 0, s[0:1]
	s_lshl_b64 s[0:1], s[10:11], 11
	s_ashr_i32 s5, s4, 31
	v_xor_b32_e32 v128, 0x80, v131
	v_cmp_eq_u32_e64 s[6:7], 0, v130
	v_lshl_add_u64 v[64:65], v[64:65], 1, s[0:1]
	s_lshl_b64 s[12:13], s[4:5], 11
	s_lshl_b64 s[14:15], s[10:11], 2
	s_lshl_b64 s[16:17], s[4:5], 2
	s_mov_b64 s[18:19], 0x1f00000
	s_mov_b64 s[20:21], 0x1f00800
	s_mov_b64 s[22:23], 0x1f01000
	s_mov_b32 s0, 0x1f01000
	s_mov_b64 s[24:25], 0x1f01800
	v_mov_b32_e32 v129, 0xda000
	v_mov_b32_e32 v130, 0xe0000
	v_mov_b32_e32 v131, 0xe5000
	v_mov_b32_e32 v132, 0xeb000
	v_mov_b32_e32 v133, 0xf0000
	s_branch .LBB0_920
